# adds: diff loop LDS-DMA in saddr form (no 64-bit address VALU), packed running row-sum, tail address adds moved under MFMA, fewer nops
# speedup vs baseline: 1.0345x; 1.0160x over previous
; #define VLOAD(dst, sbv, q) do { _Pragma("unroll") for (int d_ = 0; d_ < 4; ++d_) dst[d_] = *(const lds_bf16x8*)((sbv) + vo[q] + d_ * 4096); } while (0)
; DI void diff_unit(KP p, int l, int b, int h, int qb, int isctx, float lamv, float lam_init, char* ldsc) {
;     ...
;   float m, lsum;
;   const bf16_t* vt = p->Vtd + (size_t)((b * 4 + h) * 128) * NKEY;
;   const bf16_t* Pk = p->P + 1024 + h * 128;
;   const int row8 = 8 * w + (lane >> 3), swz = ((lane & 7) ^ ((row8 >> 1) & 7)) << 4;
;   const unsigned kq = (unsigned)(row8 * (INC * 2) + swz), vq = (unsigned)(row8 * (NKEY * 2) + swz);
;     ...
;   bf16x8 P[4];
;   {
;     f32x16 st[2];
;     qk_tile(qf, L + comp * 8192, ko, st);
;     m = tile_max(st);
;     lsum = exp_pack(st, m, P);
;   }
;   int stg = 0;
;   bool need = false; float alpha = 1.f;
;   if (w >= 4) __builtin_amdgcn_s_setprio(1);
;   bf16x8 vA[4], vB[4];
;   VLOAD(vA, L + 16384, 0); VLOAD(vB, L + 16384, 1);
.LBB0_470:
	v_and_b32_e32 v133, 63, v38
	v_max_f32_e32 v38, v43, v43
	v_max_f32_e32 v42, v42, v42
	v_max_f32_e32 v153, v42, v38
	v_sub_f32_e32 v252, 0, v153
	v_mov_b32_e32 v253, v252
	v_fma_f32 v2, v2, 1.0, -v153
	v_fma_f32 v3, v3, 1.0, -v153
	v_exp_f32_e32 v2, v2
	v_exp_f32_e32 v3, v3
	v_fma_f32 v10, v10, 1.0, -v153
	v_exp_f32_e32 v10, v10
	v_fma_f32 v11, v11, 1.0, -v153
	v_fma_f32 v4, v4, 1.0, -v153
	v_exp_f32_e32 v11, v11
	v_fma_f32 v12, v12, 1.0, -v153
	v_exp_f32_e32 v4, v4
	v_fma_f32 v5, v5, 1.0, -v153
	v_exp_f32_e32 v12, v12
	v_fma_f32 v13, v13, 1.0, -v153
	v_exp_f32_e32 v5, v5
	v_fma_f32 v6, v6, 1.0, -v153
	v_cvt_pk_bf16_f32 v66, v2, v3
	v_exp_f32_e32 v13, v13
	v_fma_f32 v14, v14, 1.0, -v153
	v_add_f32_e32 v2, 0, v2
	v_exp_f32_e32 v6, v6
	v_fma_f32 v7, v7, 1.0, -v153
	v_exp_f32_e32 v14, v14
	v_fma_f32 v15, v15, 1.0, -v153
	v_add_f32_e32 v2, v3, v2
	v_add_f32_e32 v3, 0, v10
	v_exp_f32_e32 v7, v7
	v_fma_f32 v8, v8, 1.0, -v153
	v_exp_f32_e32 v15, v15
	v_fma_f32 v16, v16, 1.0, -v153
	v_add_f32_e32 v3, v11, v3
	v_exp_f32_e32 v8, v8
	v_fma_f32 v9, v9, 1.0, -v153
	v_exp_f32_e32 v16, v16
	v_fma_f32 v17, v17, 1.0, -v153
	v_add_f32_e32 v2, v4, v2
	v_add_f32_e32 v3, v12, v3
	v_exp_f32_e32 v9, v9
	v_exp_f32_e32 v17, v17
	v_fma_f32 v18, v18, 1.0, -v153
	v_fma_f32 v26, v26, 1.0, -v153
	v_add_f32_e32 v2, v5, v2
	v_add_f32_e32 v3, v13, v3
	v_exp_f32_e32 v18, v18
	v_fma_f32 v19, v19, 1.0, -v153
	v_exp_f32_e32 v26, v26
	v_fma_f32 v27, v27, 1.0, -v153
	v_add_f32_e32 v2, v6, v2
	v_add_f32_e32 v3, v14, v3
	v_exp_f32_e32 v19, v19
	v_fma_f32 v20, v20, 1.0, -v153
	v_exp_f32_e32 v27, v27
	v_fma_f32 v28, v28, 1.0, -v153
	v_add_f32_e32 v2, v7, v2
	v_add_f32_e32 v3, v15, v3
	v_exp_f32_e32 v20, v20
	v_fma_f32 v21, v21, 1.0, -v153
	v_exp_f32_e32 v28, v28
	v_fma_f32 v29, v29, 1.0, -v153
	v_add_f32_e32 v2, v8, v2
	v_add_f32_e32 v3, v16, v3
	v_exp_f32_e32 v21, v21
	v_fma_f32 v22, v22, 1.0, -v153
	v_exp_f32_e32 v29, v29
	v_fma_f32 v30, v30, 1.0, -v153
	v_add_f32_e32 v2, v9, v2
	v_add_f32_e32 v3, v17, v3
	v_cvt_pk_bf16_f32 v67, v4, v5
	v_exp_f32_e32 v22, v22
	v_fma_f32 v23, v23, 1.0, -v153
	v_exp_f32_e32 v30, v30
	v_fma_f32 v31, v31, 1.0, -v153
	v_add_f32_e32 v2, v2, v3
	v_add_f32_e32 v3, 0, v18
	v_add_f32_e32 v4, 0, v26
	v_exp_f32_e32 v23, v23
	v_fma_f32 v24, v24, 1.0, -v153
	v_exp_f32_e32 v31, v31
	v_fma_f32 v32, v32, 1.0, -v153
	v_add_f32_e32 v3, v19, v3
	v_add_f32_e32 v4, v27, v4
	v_exp_f32_e32 v24, v24
	v_fma_f32 v25, v25, 1.0, -v153
	v_exp_f32_e32 v32, v32
	v_fma_f32 v33, v33, 1.0, -v153
	v_add_f32_e32 v3, v20, v3
	v_add_f32_e32 v4, v28, v4
	v_exp_f32_e32 v25, v25
	v_exp_f32_e32 v33, v33
	v_add_f32_e32 v3, v21, v3
	v_add_f32_e32 v4, v29, v4
	v_add_f32_e32 v3, v22, v3
	v_add_f32_e32 v4, v30, v4
	v_add_f32_e32 v3, v23, v3
	v_add_f32_e32 v4, v31, v4
	v_add_f32_e32 v3, v24, v3
	v_add_f32_e32 v4, v32, v4
	v_lshlrev_b32_e32 v35, 7, v35
	v_bitop3_b32 v38, v144, v34, 7 bitop3:0x78
	v_add_f32_e32 v3, v25, v3
	v_add_f32_e32 v4, v33, v4
	v_lshl_or_b32 v150, v38, 4, v35
	v_bitop3_b32 v38, v39, v34, 7 bitop3:0x78
	v_add_f32_e32 v3, v3, v4
	v_lshl_or_b32 v151, v38, 4, v35
	v_add_f32_e32 v152, v2, v3
	v_add_u32_e32 v2, 0, v150
	ds_read_b128 v[86:89], v2 offset:16384
	ds_read_b128 v[82:85], v2 offset:20480
	ds_read_b128 v[78:81], v2 offset:24576
	ds_read_b128 v[74:77], v2 offset:28672
	v_add_u32_e32 v2, 0, v151
	s_add_i32 s2, s18, s17
	s_mul_i32 s15, s15, 0x21000
	ds_read_b128 v[126:129], v2 offset:16384
	ds_read_b128 v[122:125], v2 offset:20480
	ds_read_b128 v[94:97], v2 offset:24576
	ds_read_b128 v[90:93], v2 offset:28672
	v_lshl_add_u64 v[136:137], s[10:11], 0, v[0:1]
	s_mov_b64 s[22:23], s[10:11]
	v_add_u32_e32 v244, 0x800, v0
	v_add_u32_e32 v245, 0x880, v0
	s_add_i32 s10, s16, 0xffffff80
	s_mul_hi_i32 s11, s2, 0x4200
	s_mulk_i32 s2, 0x4200
	v_mov_b32_e32 v0, s15
	v_mad_u32_u24 v0, v36, s65, v0
	s_add_u32 s4, s4, s2
	v_or_b32_e32 v0, v0, v37
	s_addc_u32 s5, s5, s11
	v_cvt_pk_bf16_f32 v72, v14, v15
	v_bitop3_b32 v38, v40, v34, 7 bitop3:0x78
	v_bitop3_b32 v34, v41, v34, 7 bitop3:0x78
	v_lshl_add_u64 v[2:3], s[4:5], 0, v[0:1]
	s_add_u32 s20, s4, 0x180
	s_addc_u32 s21, s5, 0
	v_mov_b32_e32 v246, v0
	v_add_u32_e32 v247, 0x108000, v0
	s_mov_b64 s[4:5], 0x108180
	v_mov_b32_e32 v14, v1
	v_mov_b32_e32 v15, v1
	v_cvt_pk_bf16_f32 v68, v6, v7
	v_cvt_pk_bf16_f32 v69, v8, v9
	v_cvt_pk_bf16_f32 v70, v10, v11
	v_cvt_pk_bf16_f32 v71, v12, v13
	v_cvt_pk_bf16_f32 v118, v18, v19
	v_cvt_pk_bf16_f32 v119, v20, v21
	v_cvt_pk_bf16_f32 v120, v22, v23
	v_cvt_pk_bf16_f32 v121, v24, v25
	v_cvt_pk_bf16_f32 v114, v26, v27
	v_cvt_pk_bf16_f32 v115, v28, v29
	v_cvt_pk_bf16_f32 v116, v30, v31
	v_cvt_pk_bf16_f32 v117, v32, v33
	v_lshl_or_b32 v149, v38, 4, v35
	v_lshl_or_b32 v146, v34, 4, v35
	v_lshl_add_u64 v[138:139], v[2:3], 0, s[4:5]
	v_mov_b32_e32 v0, v1
	v_mov_b32_e32 v2, v1
	v_mov_b32_e32 v3, v1
	v_mov_b32_e32 v4, v1
	v_mov_b32_e32 v5, v1
	v_mov_b32_e32 v6, v1
	v_mov_b32_e32 v7, v1
	v_mov_b32_e32 v8, v1
	v_mov_b32_e32 v9, v1
	v_mov_b32_e32 v10, v1
	v_mov_b32_e32 v11, v1
	v_mov_b32_e32 v12, v1
	v_mov_b32_e32 v13, v1
	v_mov_b64_e32 v[64:65], v[14:15]
	v_mov_b64_e32 v[48:49], v[14:15]
	v_mov_b64_e32 v[32:33], v[14:15]
	v_cvt_pk_bf16_f32 v73, v16, v17
	v_mov_b64_e32 v[62:63], v[12:13]
	v_mov_b64_e32 v[60:61], v[10:11]
	v_mov_b64_e32 v[58:59], v[8:9]
	v_mov_b64_e32 v[56:57], v[6:7]
	v_mov_b64_e32 v[54:55], v[4:5]
	v_mov_b64_e32 v[52:53], v[2:3]
	v_mov_b64_e32 v[50:51], v[0:1]
	v_mov_b64_e32 v[46:47], v[12:13]
	v_mov_b64_e32 v[44:45], v[10:11]
	v_mov_b64_e32 v[42:43], v[8:9]
	v_mov_b64_e32 v[40:41], v[6:7]
	v_mov_b64_e32 v[38:39], v[4:5]
	v_mov_b64_e32 v[36:37], v[2:3]
	v_mov_b64_e32 v[34:35], v[0:1]
	v_mov_b64_e32 v[30:31], v[12:13]
	v_mov_b64_e32 v[28:29], v[10:11]
	v_mov_b64_e32 v[26:27], v[8:9]
	v_mov_b64_e32 v[24:25], v[6:7]
	v_mov_b64_e32 v[22:23], v[4:5]
	v_mov_b64_e32 v[20:21], v[2:3]
	v_mov_b64_e32 v[18:19], v[0:1]
	v_mov_b64_e32 v[16:17], v[14:15]
	v_ashrrev_i32_e32 v135, 31, v134
	v_mov_b32_e32 v140, 1.0
	s_mov_b64 s[4:5], 0
	s_mov_b32 s17, 0
	v_mov_b64_e32 v[14:15], v[12:13]
	v_mov_b64_e32 v[12:13], v[10:11]
	v_mov_b64_e32 v[10:11], v[8:9]
	v_mov_b64_e32 v[8:9], v[6:7]
	v_mov_b64_e32 v[6:7], v[4:5]
	v_mov_b64_e32 v[4:5], v[2:3]
	v_mov_b64_e32 v[2:3], v[0:1]
	s_mov_b32 s11, 0
	v_mov_b32_e32 v153, 0

; #define MFMA32(a, b, c) __builtin_amdgcn_mfma_f32_32x32x16_bf16((a), (b), (c), 0, 0, 0)
; #define VLOAD(dst, sbv, q) do { _Pragma("unroll") for (int d_ = 0; d_ < 4; ++d_) dst[d_] = *(const lds_bf16x8*)((sbv) + vo[q] + d_ * 4096); } while (0)
; #define FENCE __builtin_amdgcn_sched_barrier(0)
; DI void diff_unit(KP p, int l, int b, int h, int qb, int isctx, float lamv, float lam_init, char* ldsc) {
;     ...
;     asm volatile("s_waitcnt vmcnt(0)" ::: "memory");
;     __builtin_amdgcn_s_barrier();
;     const int stg1 = stg == 2 ? 0 : stg + 1;
;     if (kt + 2 < nt) { const int s2_ = stg >= 1 ? stg - 1 : 2; DISSUE(kt + 2, s2_); }
;     if (need) {
; #pragma unroll
;       for (int d = 0; d < 4; ++d) o[d] *= alpha;
;     }
;     const lds_u8* sbv = L + stg * STG + 16384;
;     const lds_u8* sbk = L + stg1 * STG + comp * 8192;
;     bf16x8 kf[2][4];
;     f32x16 st[2];
; #pragma unroll
;     for (int t = 0; t < 2; ++t)
; #pragma unroll
;       for (int ks = 0; ks < 4; ++ks) kf[t][ks] = *(const lds_bf16x8*)(sbk + ko[ks] + t * 4096);
;     FENCE;
;     pv_grp(o, vA, P[0]); pv_grp(o, vB, P[1]);
;     VLOAD(vA, sbv, 2); VLOAD(vB, sbv, 3);
;     FENCE;
; #pragma unroll
;     for (int i = 0; i < 16; ++i) { st[0][i] = 0.f; st[1][i] = 0.f; }
; #pragma unroll
;     for (int ks = 0; ks < 4; ++ks) st[0] = MFMA32(kf[0][ks], qf[ks], st[0]);
; #pragma unroll
;     for (int ks = 0; ks < 4; ++ks) st[1] = MFMA32(kf[1][ks], qf[ks], st[1]);
;     FENCE;
;     pv_grp(o, vA, P[2]);
;     const float mx = tile_max(st);
;     need = !__all(mx <= m + 8.0f);
;     const float mn = need ? fmaxf(m, mx) : m;
;     alpha = __builtin_amdgcn_exp2f(m - mn);
;     FENCE;
.LBB0_477:
	s_add_i32 s2, s17, 1
	s_and_b32 s16, s2, 3
	s_lshl_b32 s2, s16, 15
	s_add_i32 s15, s2, 0
	s_add_i32 s2, s15, s14
	v_add_u32_e32 v0, s2, v141
	v_add_u32_e32 v251, s2, v145
	v_add_u32_e32 v191, s2, v147
	v_add_u32_e32 v216, s2, v148
	ds_read_b128 v[154:157], v0
	ds_read_b128 v[192:195], v0 offset:4096
	ds_read_b128 v[196:199], v251
	ds_read_b128 v[200:203], v251 offset:4096
	ds_read_b128 v[204:207], v191
	ds_read_b128 v[208:211], v191 offset:4096
	ds_read_b128 v[212:215], v216
	ds_read_b128 v[216:219], v216 offset:4096
	s_lshl_b32 s2, s17, 15
	s_add_i32 s2, s2, 0
	s_waitcnt lgkmcnt(8)
	v_mfma_f32_32x32x16_bf16 v[50:65], v[86:89], v[66:69], v[50:65]
	v_add_u32_e32 v0, s2, v149
	ds_read_b128 v[220:223], v0 offset:24576
	ds_read_b128 v[224:227], v0 offset:28672
	s_add_i32 s18, s3, 0xc0
	s_add_i32 s19, s10, 64
	s_cmp_eq_u32 s11, 0
	s_cselect_b32 s19, s18, s19
	s_mul_i32 s19, s19, 0x1600
	s_add_u32 s18, s22, s19
	s_addc_u32 s19, s23, 0
	s_add_i32 s24, s17, 3
	s_and_b32 s24, s24, 3
	s_lshl_b32 s24, s24, 15
	s_add_i32 s24, s13, s24
	s_mov_b32 m0, s24
	v_mfma_f32_32x32x16_bf16 v[34:49], v[82:85], v[66:69], v[34:49]
	global_load_lds_dwordx4 v244, s[18:19]
	s_add_i32 m0, s24, 0x2000
	v_mfma_f32_32x32x16_bf16 v[18:33], v[78:81], v[66:69], v[18:33]
	v_mfma_f32_32x32x16_bf16 v[2:17], v[74:77], v[66:69], v[2:17]
	v_mov_b64_e32 v[66:67], v[252:253]
	v_mov_b64_e32 v[68:69], v[252:253]
	v_mov_b64_e32 v[74:75], v[252:253]
	global_load_lds_dwordx4 v245, s[18:19]
	s_add_i32 m0, s24, 0x4000
	v_mfma_f32_32x32x16_bf16 v[50:65], v[126:129], v[70:73], v[50:65]
	v_mov_b64_e32 v[76:77], v[252:253]
	v_mov_b64_e32 v[78:79], v[252:253]
	v_mov_b64_e32 v[80:81], v[252:253]
	ds_read_b128 v[126:129], v0 offset:20480
	v_mfma_f32_32x32x16_bf16 v[34:49], v[122:125], v[70:73], v[34:49]
	v_mov_b64_e32 v[82:83], v[252:253]
	v_mov_b64_e32 v[84:85], v[252:253]
	ds_read_b128 v[122:125], v0 offset:16384
	v_add_u32_e32 v0, s2, v146
	ds_read_b128 v[228:231], v0 offset:16384
	ds_read_b128 v[232:235], v0 offset:20480
	ds_read_b128 v[236:239], v0 offset:24576
	ds_read_b128 v[240:243], v0 offset:28672
	v_mfma_f32_32x32x16_bf16 v[18:33], v[94:97], v[70:73], v[18:33]
	v_mov_b64_e32 v[86:87], v[252:253]
	v_mov_b64_e32 v[88:89], v[252:253]
	v_mov_b64_e32 v[94:95], v[252:253]
	v_mov_b64_e32 v[96:97], v[252:253]
	v_mfma_f32_32x32x16_bf16 v[2:17], v[90:93], v[70:73], v[2:17]
	v_mov_b64_e32 v[70:71], v[252:253]
	v_mov_b64_e32 v[72:73], v[252:253]
	v_mov_b64_e32 v[90:91], v[252:253]
	v_mov_b64_e32 v[92:93], v[252:253]
	global_load_lds_dwordx4 v246, s[20:21]
	s_add_i32 m0, s24, 0x6000
	s_waitcnt lgkmcnt(8)
	v_mfma_f32_32x32x16_bf16 v[66:81], v[192:195], v[98:101], v[66:81]
	v_mfma_f32_32x32x16_bf16 v[82:97], v[154:157], v[98:101], v[82:97]
	v_mfma_f32_32x32x16_bf16 v[66:81], v[200:203], v[102:105], v[66:81]
	v_mfma_f32_32x32x16_bf16 v[82:97], v[196:199], v[102:105], v[82:97]
	global_load_lds_dwordx4 v247, s[20:21]
	s_add_u32 s20, s20, 0x80
	s_addc_u32 s21, s21, 0
	v_mfma_f32_32x32x16_bf16 v[66:81], v[208:211], v[106:109], v[66:81]
	v_mfma_f32_32x32x16_bf16 v[82:97], v[204:207], v[106:109], v[82:97]
	v_mfma_f32_32x32x16_bf16 v[66:81], v[216:219], v[110:113], v[66:81]
	v_mfma_f32_32x32x16_bf16 v[82:97], v[212:215], v[110:113], v[82:97]
	s_waitcnt lgkmcnt(0)
	v_mfma_f32_32x32x16_bf16 v[50:65], v[122:125], v[118:121], v[50:65]
	v_add_u32_e32 v251, s15, v150
	v_add_u32_e32 v249, s15, v151
	s_nop 7
	v_max3_f32 v0, v82, v83, v84
	v_max3_f32 v250, v66, v67, v68
	v_mfma_f32_32x32x16_bf16 v[34:49], v[126:129], v[118:121], v[34:49]
	v_max3_f32 v0, v0, v85, v86
	v_max3_f32 v250, v250, v69, v70
	v_max3_f32 v0, v0, v87, v88
	v_max3_f32 v250, v250, v71, v72
	v_max3_f32 v0, v0, v89, v90
	v_mfma_f32_32x32x16_bf16 v[18:33], v[220:223], v[118:121], v[18:33]
	v_max3_f32 v250, v250, v73, v74
	v_max3_f32 v0, v0, v91, v92
	v_max3_f32 v250, v250, v75, v76
	v_max3_f32 v0, v0, v93, v94
	v_max3_f32 v250, v250, v77, v78
	v_mfma_f32_32x32x16_bf16 v[2:17], v[224:227], v[118:121], v[2:17]
	v_max3_f32 v0, v0, v95, v96
	v_max3_f32 v250, v250, v79, v80
	v_max_f32_e32 v0, v0, v97
	v_max_f32_e32 v250, v250, v81
	v_max_f32_e32 v0, v0, v250
	v_mov_b32_e32 v118, v0
	s_nop 1
	v_permlane32_swap_b32_e32 v0, v118
	v_max_f32_e32 v0, v0, v118
	v_cmp_ge_f32_e32 vcc, 0x41000000, v0
	s_cmp_lg_u64 vcc, exec
	s_cselect_b64 s[4:5], -1, 0
	s_cbranch_scc0 .Ldiff_nosub
	v_max_f32_e32 v0, 0, v0
	v_sub_f32_e32 v252, v252, v0
	v_exp_f32_e64 v140, -v0
	v_mov_b32_e32 v253, v252
	v_pk_mul_f32 v[152:153], v[152:153], v[140:141] op_sel_hi:[1,0]
	v_sub_f32_e32 v82, v82, v0
	v_sub_f32_e32 v83, v83, v0
	v_sub_f32_e32 v84, v84, v0
	v_sub_f32_e32 v85, v85, v0
	v_sub_f32_e32 v86, v86, v0
	v_sub_f32_e32 v87, v87, v0
	v_sub_f32_e32 v88, v88, v0
	v_sub_f32_e32 v89, v89, v0
	v_sub_f32_e32 v90, v90, v0
	v_sub_f32_e32 v91, v91, v0
	v_sub_f32_e32 v92, v92, v0
	v_sub_f32_e32 v93, v93, v0
	v_sub_f32_e32 v94, v94, v0
	v_sub_f32_e32 v95, v95, v0
	v_sub_f32_e32 v96, v96, v0
	v_sub_f32_e32 v97, v97, v0
	v_sub_f32_e32 v66, v66, v0
	v_sub_f32_e32 v67, v67, v0
	v_sub_f32_e32 v68, v68, v0
	v_sub_f32_e32 v69, v69, v0
	v_sub_f32_e32 v70, v70, v0
	v_sub_f32_e32 v71, v71, v0
	v_sub_f32_e32 v72, v72, v0
	v_sub_f32_e32 v73, v73, v0
	v_sub_f32_e32 v74, v74, v0
	v_sub_f32_e32 v75, v75, v0
	v_sub_f32_e32 v76, v76, v0
	v_sub_f32_e32 v77, v77, v0
	v_sub_f32_e32 v78, v78, v0
	v_sub_f32_e32 v79, v79, v0
	v_sub_f32_e32 v80, v80, v0
	v_sub_f32_e32 v81, v81, v0
; #define VLOAD(dst, sbv, q) do { _Pragma("unroll") for (int d_ = 0; d_ < 4; ++d_) dst[d_] = *(const lds_bf16x8*)((sbv) + vo[q] + d_ * 4096); } while (0)
; #define FENCE __builtin_amdgcn_sched_barrier(0)
; DI void diff_unit(KP p, int l, int b, int h, int qb, int isctx, float lamv, float lam_init, char* ldsc) {
;     ...
;     float ps = exp_pack1<0>(st, mn, P[0]);
;     ps += exp_pack1<1>(st, mn, P[1]);
;     ps += exp_pack1<2>(st, mn, P[2]);
;     pv_grp(o, vB, P[3]);
;     ps += exp_pack1<3>(st, mn, P[3]);
; #pragma unroll
;     for (int q = 0; q < 4; ++q) { __builtin_amdgcn_sched_group_barrier(0x402, 18, 0); __builtin_amdgcn_sched_group_barrier(0x008, 1, 0); }
;     lsum = lsum * alpha + ps; m = mn;
;     FENCE;
;     { const lds_u8* sbn = L + stg1 * STG + 16384; VLOAD(vA, sbn, 0); VLOAD(vB, sbn, 1); }
;     stg = stg1;
;   }
;   __builtin_amdgcn_s_setprio(0);
;   if (need) {
; #pragma unroll
;     for (int d = 0; d < 4; ++d) o[d] *= alpha;
;   }
.Ldiff_nosub:
	v_exp_f32_e32 v122, v82
	v_exp_f32_e32 v124, v83
	v_exp_f32_e32 v126, v84
	v_exp_f32_e32 v128, v85
	v_exp_f32_e32 v156, v86
	v_exp_f32_e32 v192, v87
	v_exp_f32_e32 v194, v88
	v_exp_f32_e32 v196, v89
	v_exp_f32_e32 v123, v90
	v_mfma_f32_32x32x16_bf16 v[50:65], v[228:231], v[114:117], v[50:65]
	v_exp_f32_e32 v125, v91
	v_exp_f32_e32 v127, v92
	v_exp_f32_e32 v129, v93
	v_exp_f32_e32 v157, v94
	v_exp_f32_e32 v193, v95
	v_exp_f32_e32 v195, v96
	v_exp_f32_e32 v197, v97
	v_exp_f32_e32 v83, v66
	v_exp_f32_e32 v67, v67
	v_mfma_f32_32x32x16_bf16 v[34:49], v[232:235], v[114:117], v[34:49]
	v_exp_f32_e32 v85, v68
	v_exp_f32_e32 v69, v69
	v_exp_f32_e32 v87, v70
	v_exp_f32_e32 v71, v71
	v_exp_f32_e32 v89, v72
	v_exp_f32_e32 v73, v73
	v_exp_f32_e32 v82, v74
	v_exp_f32_e32 v66, v75
	v_exp_f32_e32 v84, v76
	v_mfma_f32_32x32x16_bf16 v[18:33], v[236:239], v[114:117], v[18:33]
	v_exp_f32_e32 v68, v77
	v_exp_f32_e32 v86, v78
	v_exp_f32_e32 v70, v79
	v_exp_f32_e32 v88, v80
	v_exp_f32_e32 v72, v81
	v_mfma_f32_32x32x16_bf16 v[2:17], v[240:243], v[114:117], v[2:17]
	v_cvt_pk_bf16_f32 v118, v83, v67
	v_cvt_pk_bf16_f32 v114, v82, v66
	v_pk_add_f32 v[66:67], v[66:67], v[82:83]
	v_cvt_pk_bf16_f32 v119, v85, v69
	v_pk_add_f32 v[66:67], v[84:85], v[66:67]
	v_cvt_pk_bf16_f32 v120, v87, v71
	v_pk_add_f32 v[66:67], v[68:69], v[66:67]
	v_cvt_pk_bf16_f32 v121, v89, v73
	v_pk_add_f32 v[66:67], v[86:87], v[66:67]
	v_cvt_pk_bf16_f32 v115, v84, v68
	v_pk_add_f32 v[66:67], v[70:71], v[66:67]
	v_cvt_pk_bf16_f32 v116, v86, v70
	v_pk_add_f32 v[66:67], v[88:89], v[66:67]
	v_cvt_pk_bf16_f32 v117, v88, v72
	v_pk_add_f32 v[90:91], v[72:73], v[66:67]
	v_pk_add_f32 v[92:93], v[124:125], v[122:123]
	ds_read_b128 v[86:89], v251 offset:16384
	ds_read_b128 v[82:85], v251 offset:20480
	v_pk_add_f32 v[92:93], v[126:127], v[92:93]
	ds_read_b128 v[78:81], v251 offset:24576
	ds_read_b128 v[74:77], v251 offset:28672
	v_pk_add_f32 v[92:93], v[128:129], v[92:93]
	v_cvt_pk_bf16_f32 v66, v122, v124
	v_pk_add_f32 v[92:93], v[156:157], v[92:93]
	v_cvt_pk_bf16_f32 v67, v126, v128
	v_pk_add_f32 v[92:93], v[192:193], v[92:93]
	v_cvt_pk_bf16_f32 v70, v123, v125
	v_pk_add_f32 v[92:93], v[194:195], v[92:93]
	v_cvt_pk_bf16_f32 v71, v127, v129
	v_pk_add_f32 v[92:93], v[196:197], v[92:93]
	s_add_i32 s11, s11, 1
	v_pk_add_f32 v[152:153], v[152:153], v[92:93]
	v_pk_add_f32 v[152:153], v[152:153], v[90:91]
	ds_read_b128 v[126:129], v249 offset:16384
	ds_read_b128 v[122:125], v249 offset:20480
	ds_read_b128 v[94:97], v249 offset:24576
	ds_read_b128 v[90:93], v249 offset:28672
	s_add_i32 s10, s10, 64
	v_cvt_pk_bf16_f32 v68, v156, v192
	v_cvt_pk_bf16_f32 v69, v194, v196
	v_cvt_pk_bf16_f32 v72, v157, v193
	v_cvt_pk_bf16_f32 v73, v195, v197
	s_cmpk_eq_i32 s11, 0x83
	s_cbranch_scc1 .LBB0_479
	s_mov_b32 s17, s16
	s_branch .LBB0_471
.LBB0_479:
	v_add_f32_e32 v0, v152, v153
	s_setprio 0
	s_andn2_b64 vcc, exec, s[4:5]
	s_cbranch_vccnz .LBB0_481
	v_pk_mul_f32 v[64:65], v[64:65], v[140:141] op_sel_hi:[1,0]
	v_pk_mul_f32 v[62:63], v[62:63], v[140:141] op_sel_hi:[1,0]
	v_pk_mul_f32 v[60:61], v[60:61], v[140:141] op_sel_hi:[1,0]
	v_pk_mul_f32 v[58:59], v[58:59], v[140:141] op_sel_hi:[1,0]
	v_pk_mul_f32 v[56:57], v[56:57], v[140:141] op_sel_hi:[1,0]
	v_pk_mul_f32 v[54:55], v[54:55], v[140:141] op_sel_hi:[1,0]
	v_pk_mul_f32 v[52:53], v[52:53], v[140:141] op_sel_hi:[1,0]
	v_pk_mul_f32 v[50:51], v[50:51], v[140:141] op_sel_hi:[1,0]
	v_pk_mul_f32 v[48:49], v[48:49], v[140:141] op_sel_hi:[1,0]
	v_pk_mul_f32 v[46:47], v[46:47], v[140:141] op_sel_hi:[1,0]
	v_pk_mul_f32 v[44:45], v[44:45], v[140:141] op_sel_hi:[1,0]
	v_pk_mul_f32 v[42:43], v[42:43], v[140:141] op_sel_hi:[1,0]
	v_pk_mul_f32 v[40:41], v[40:41], v[140:141] op_sel_hi:[1,0]
	v_pk_mul_f32 v[38:39], v[38:39], v[140:141] op_sel_hi:[1,0]
	v_pk_mul_f32 v[36:37], v[36:37], v[140:141] op_sel_hi:[1,0]
	v_pk_mul_f32 v[34:35], v[34:35], v[140:141] op_sel_hi:[1,0]
	v_pk_mul_f32 v[32:33], v[32:33], v[140:141] op_sel_hi:[1,0]
	v_pk_mul_f32 v[30:31], v[30:31], v[140:141] op_sel_hi:[1,0]
	v_pk_mul_f32 v[28:29], v[28:29], v[140:141] op_sel_hi:[1,0]
	v_pk_mul_f32 v[26:27], v[26:27], v[140:141] op_sel_hi:[1,0]
	v_pk_mul_f32 v[24:25], v[24:25], v[140:141] op_sel_hi:[1,0]
	v_pk_mul_f32 v[22:23], v[22:23], v[140:141] op_sel_hi:[1,0]
	v_pk_mul_f32 v[20:21], v[20:21], v[140:141] op_sel_hi:[1,0]
	v_pk_mul_f32 v[18:19], v[18:19], v[140:141] op_sel_hi:[1,0]
	v_pk_mul_f32 v[16:17], v[16:17], v[140:141] op_sel_hi:[1,0]
	v_pk_mul_f32 v[14:15], v[14:15], v[140:141] op_sel_hi:[1,0]
	v_pk_mul_f32 v[12:13], v[12:13], v[140:141] op_sel_hi:[1,0]
	v_pk_mul_f32 v[10:11], v[10:11], v[140:141] op_sel_hi:[1,0]
	v_pk_mul_f32 v[8:9], v[8:9], v[140:141] op_sel_hi:[1,0]
	v_pk_mul_f32 v[6:7], v[6:7], v[140:141] op_sel_hi:[1,0]
	v_pk_mul_f32 v[4:5], v[4:5], v[140:141] op_sel_hi:[1,0]
	v_pk_mul_f32 v[2:3], v[2:3], v[140:141] op_sel_hi:[1,0]
